# attention staging block: three counted vmcnt waits consolidated into one before the LDS writes (fast loop)
# baseline (speedup 1.0000x reference)
; #define SBAR() __builtin_amdgcn_sched_barrier(0)
; #define PK4(P, BASE, OUT) do { u32x4 w = {cvt_pk_bf16(P[BASE + 0], P[BASE + 1]), cvt_pk_bf16(P[BASE + 2], P[BASE + 3]), cvt_pk_bf16(P[BASE + 4], P[BASE + 5]), cvt_pk_bf16(P[BASE + 6], P[BASE + 7])}; \
;     OUT = *reinterpret_cast<bf16x8*>(&w); } while (0)
; __device__ __forceinline__ void finishSM(f32x16& p0, f32x16& p1, float alpha, float& l_reg, bf16x8& pa0, bf16x8& pa1, bf16x8& pa2, bf16x8& pa3) {
; #pragma unroll
;   for (int r = 0; r < 16; ++r) p1[r] = __builtin_amdgcn_exp2f(p1[r]);
;   float ps = 0;
; #pragma unroll
;   for (int r = 0; r < 16; ++r) ps += p0[r];
; #pragma unroll
;   for (int r = 0; r < 16; ++r) ps += p1[r];
;   { auto rr = __builtin_amdgcn_permlane32_swap(__float_as_uint(ps), __float_as_uint(ps), false, false);
;     ps = __uint_as_float(rr[0]) + __uint_as_float(rr[1]); }
;   l_reg = l_reg * alpha + ps;
;     ...
;   PK4(p0, 0, pa0); PK4(p0, 8, pa1); PK4(p1, 0, pa2); PK4(p1, 8, pa3);
;     ...
; }
; __device__ __forceinline__ void qkt(f32x16& p0, f32x16& p1, const char* Ks, const bf16x8* qr, const f32x16& negm, int r32, int hi) {
;   p0 = negm; p1 = negm;
; #pragma unroll
;   for (int d0 = 0; d0 < 6; ++d0) { int cb = (d0 * 16 + hi * 8) * 2;
;     bf16x8 b0 = *reinterpret_cast<const bf16x8*>(Ks + KSWZ(r32, cb));
;     bf16x8 b1 = *reinterpret_cast<const bf16x8*>(Ks + KSWZ(32 + r32, cb));
;     p0 = __builtin_amdgcn_mfma_f32_32x32x16_bf16(b0, qr[d0], p0, 0, 0, 0);
;     p1 = __builtin_amdgcn_mfma_f32_32x32x16_bf16(b1, qr[d0], p1, 0, 0, 0); }
; }
; __device__ __forceinline__ void attn_unit(const bf16_t* __restrict__ Qb, const bf16_t* __restrict__ KNh, const bf16_t* __restrict__ KRb, const bf16_t* __restrict__ Vh, bf16_t* __restrict__ Ob, char* lds) {
;     ...
;     SBAR(); qkt(pB0, pB1, K_lds + (j & 3) * SHM_K, qr, negm, r32, hi);
;     finishSM(pA0, pA1, alA, l_reg, pa0, pa1, pa2, pa3); SBAR();
;     if (j + 2 < NT) { SWRITE((j + 2) & 3, 1); } if (j + 3 < NT) { SLOAD(0, (j + 3) * KVBLK); } SBAR();
;     pv_d0(o, vb0 + ((j - 1) & 3) * SHM_V, pa0, pa1, pa2, pa3); partialSM<false>(pB0, pB1, mref, negm, alB);
;     RESC(alB); ABAR();
;     SBAR(); qkt(pA0, pA1, K_lds + ((j + 1) & 3) * SHM_K, qr, negm, r32, hi);
;     finishSM(pB0, pB1, alB, l_reg, pa0, pa1, pa2, pa3); SBAR();
;     if (j + 3 < NT) { SWRITE((j + 3) & 3, 0); } if (j + 4 < NT) { SLOAD(1, (j + 4) * KVBLK); } SBAR();
.Lattn_f4:
	ds_read_b128 v[48:51], v243 offset:16384
	ds_read_b128 v[52:55], v243 offset:24576
	s_waitcnt lgkmcnt(1)
	v_mfma_f32_32x32x16_bf16 v[96:111], v[48:51], v[132:135], v[32:47]
	ds_read_b128 v[48:51], v244 offset:16384
	ds_read_b128 v[56:59], v244 offset:24576
	v_exp_f32_e32 v64, v64
	v_exp_f32_e32 v65, v65
	v_exp_f32_e32 v66, v66
	v_exp_f32_e32 v67, v67
	v_exp_f32_e32 v68, v68
	s_waitcnt lgkmcnt(2)
	v_mfma_f32_32x32x16_bf16 v[80:95], v[52:55], v[132:135], v[32:47]
	ds_read_b128 v[52:55], v245 offset:16384
	ds_read_b128 v[60:63], v245 offset:24576
	ds_read_b128 v[220:223], v246 offset:16384
	ds_read_b128 v[224:227], v246 offset:24576
	ds_read_b128 v[228:231], v247 offset:16384
	ds_read_b128 v[232:235], v247 offset:24576
	v_exp_f32_e32 v69, v69
	v_exp_f32_e32 v70, v70
	v_exp_f32_e32 v71, v71
	v_exp_f32_e32 v72, v72
	v_exp_f32_e32 v73, v73
	s_waitcnt lgkmcnt(7)
	v_mfma_f32_32x32x16_bf16 v[96:111], v[48:51], v[128:131], v[96:111]
	ds_read_b128 v[48:51], v248 offset:16384
	ds_read_b128 v[236:239], v248 offset:24576
	v_exp_f32_e32 v74, v74
	v_exp_f32_e32 v75, v75
	v_exp_f32_e32 v76, v76
	v_exp_f32_e32 v77, v77
	v_exp_f32_e32 v78, v78
	v_exp_f32_e32 v79, v79
	s_waitcnt lgkmcnt(8)
	v_mfma_f32_32x32x16_bf16 v[80:95], v[56:59], v[128:131], v[80:95]
	s_waitcnt lgkmcnt(7)
	v_mfma_f32_32x32x16_bf16 v[96:111], v[52:55], v[124:127], v[96:111]
	v_fma_f32 v52, v163, v152, v194
	v_add_f32_e32 v52, v216, v52
	v_add_f32_e32 v52, v192, v52
	v_add_f32_e32 v52, v195, v52
	v_add_f32_e32 v52, v190, v52
	v_add_f32_e32 v52, v193, v52
	v_add_f32_e32 v52, v189, v52
	s_waitcnt lgkmcnt(6)
	v_mfma_f32_32x32x16_bf16 v[80:95], v[60:63], v[124:127], v[80:95]
	v_add_f32_e32 v52, v191, v52
	v_add_f32_e32 v52, v186, v52
	v_add_f32_e32 v52, v188, v52
	v_add_f32_e32 v52, v185, v52
	v_add_f32_e32 v52, v187, v52
	v_add_f32_e32 v52, v181, v52
	v_add_f32_e32 v52, v183, v52
	s_waitcnt lgkmcnt(5)
	v_mfma_f32_32x32x16_bf16 v[96:111], v[220:223], v[120:123], v[96:111]
	v_add_f32_e32 v52, v180, v52
	v_add_f32_e32 v52, v182, v52
	v_add_f32_e32 v52, v64, v52
	v_add_f32_e32 v52, v65, v52
	v_add_f32_e32 v52, v66, v52
	v_add_f32_e32 v52, v67, v52
	v_add_f32_e32 v52, v68, v52
	s_waitcnt lgkmcnt(4)
	v_mfma_f32_32x32x16_bf16 v[80:95], v[224:227], v[120:123], v[80:95]
	v_add_f32_e32 v52, v69, v52
	v_add_f32_e32 v52, v70, v52
	v_add_f32_e32 v52, v71, v52
	v_add_f32_e32 v52, v72, v52
	v_add_f32_e32 v52, v73, v52
	v_add_f32_e32 v52, v74, v52
	v_add_f32_e32 v52, v75, v52
	s_waitcnt lgkmcnt(3)
	v_mfma_f32_32x32x16_bf16 v[96:111], v[228:231], v[116:119], v[96:111]
	v_add_f32_e32 v52, v76, v52
	v_add_f32_e32 v52, v77, v52
	v_add_f32_e32 v52, v78, v52
	v_add_f32_e32 v165, v79, v52
	s_waitcnt lgkmcnt(2)
	v_mfma_f32_32x32x16_bf16 v[80:95], v[232:235], v[116:119], v[80:95]
	v_cvt_pk_bf16_f32 v60, v194, v216
	v_cvt_pk_bf16_f32 v61, v192, v195
	v_cvt_pk_bf16_f32 v62, v190, v193
	v_cvt_pk_bf16_f32 v63, v189, v191
	v_cvt_pk_bf16_f32 v56, v186, v188
	v_cvt_pk_bf16_f32 v57, v185, v187
	v_cvt_pk_bf16_f32 v58, v181, v183
	s_waitcnt lgkmcnt(1)
	v_mfma_f32_32x32x16_bf16 v[96:111], v[48:51], v[112:115], v[96:111]
	v_cvt_pk_bf16_f32 v59, v180, v182
	v_cvt_pk_bf16_f32 v52, v64, v65
	v_cvt_pk_bf16_f32 v53, v66, v67
	v_cvt_pk_bf16_f32 v54, v68, v69
	v_cvt_pk_bf16_f32 v55, v70, v71
	v_cvt_pk_bf16_f32 v48, v72, v73
	v_cvt_pk_bf16_f32 v49, v74, v75
	s_waitcnt lgkmcnt(0)
	v_mfma_f32_32x32x16_bf16 v[80:95], v[236:239], v[112:115], v[80:95]
	v_cvt_pk_bf16_f32 v50, v76, v77
	v_cvt_pk_bf16_f32 v51, v78, v79
	s_waitcnt vmcnt(0)
	ds_write_b128 v204, v[144:147] offset:49152
	ds_write_b128 v249, v[148:151] offset:49152
	ds_write_b64 v250, v[174:175] offset:49152
	global_load_dwordx4 v[136:139], v240, s[98:99]
	global_load_dwordx4 v[140:143], v241, s[98:99]
	global_load_dwordx2 v[172:173], v242, s[100:101]
	s_add_u32 s98, s98, 0x10000
	s_addc_u32 s99, s99, 0
	s_add_u32 s100, s100, 0x1000
	s_addc_u32 s101, s101, 0

; template <bool FIRST> __device__ __forceinline__ void partialSM(f32x16& p0, f32x16& p1, float& mref, f32x16& negm, float& alpha) {
;   constexpr float THRL = THR * 1.4426950408889634f;
;   float pmax = p0[0];
; #pragma unroll
;   for (int r = 1; r < 16; ++r) pmax = fmaxf(pmax, p0[r]);
; #pragma unroll
;   for (int r = 0; r < 16; ++r) pmax = fmaxf(pmax, p1[r]);
;   { auto rr = __builtin_amdgcn_permlane32_swap(__float_as_uint(pmax), __float_as_uint(pmax), false, false);
;     pmax = fmaxf(__uint_as_float(rr[0]), __uint_as_float(rr[1])); }
;   if (!FIRST && __builtin_expect(__all(pmax <= THRL), 1)) { alpha = 1.f; }
;   else { const float dl = FIRST ? pmax : fmaxf(pmax, 0.f); mref += dl; alpha = FIRST ? 1.f : __builtin_amdgcn_exp2f(-dl);
; #pragma unroll
;     for (int r = 0; r < 16; ++r) { p0[r] -= dl; p1[r] -= dl; }
;     const float nm = -mref;
; #pragma unroll
;     for (int r = 0; r < 16; ++r) negm[r] = nm; }
; #pragma unroll
;   for (int r = 0; r < 16; ++r) p0[r] = __builtin_amdgcn_exp2f(p0[r]);
; }
; __device__ __forceinline__ void finishSM(f32x16& p0, f32x16& p1, float alpha, float& l_reg, bf16x8& pa0, bf16x8& pa1, bf16x8& pa2, bf16x8& pa3) {
; #pragma unroll
;   for (int r = 0; r < 16; ++r) p1[r] = __builtin_amdgcn_exp2f(p1[r]);
;   float ps = 0;
; #pragma unroll
;   for (int r = 0; r < 16; ++r) ps += p0[r];
; #pragma unroll
;   for (int r = 0; r < 16; ++r) ps += p1[r];
;   { auto rr = __builtin_amdgcn_permlane32_swap(__float_as_uint(ps), __float_as_uint(ps), false, false);
;     ps = __uint_as_float(rr[0]) + __uint_as_float(rr[1]); }
;   l_reg = l_reg * alpha + ps;
;     ...
;   PK4(p0, 0, pa0); PK4(p0, 8, pa1); PK4(p1, 0, pa2); PK4(p1, 8, pa3);
;     ...
; }
; __device__ __forceinline__ void qkt(f32x16& p0, f32x16& p1, const char* Ks, const bf16x8* qr, const f32x16& negm, int r32, int hi) {
;   p0 = negm; p1 = negm;
; #pragma unroll
;   for (int d0 = 0; d0 < 6; ++d0) { int cb = (d0 * 16 + hi * 8) * 2;
;     bf16x8 b0 = *reinterpret_cast<const bf16x8*>(Ks + KSWZ(r32, cb));
;     bf16x8 b1 = *reinterpret_cast<const bf16x8*>(Ks + KSWZ(32 + r32, cb));
;     p0 = __builtin_amdgcn_mfma_f32_32x32x16_bf16(b0, qr[d0], p0, 0, 0, 0);
;     p1 = __builtin_amdgcn_mfma_f32_32x32x16_bf16(b1, qr[d0], p1, 0, 0, 0); }
; }
.Lf1_746:
	s_waitcnt lgkmcnt(0)
	s_barrier
	ds_read_b128 v[64:67], v243 offset:32768
	ds_read_b128 v[184:187], v243 offset:40960
	v_exp_f32_e32 v192, v96
	v_exp_f32_e32 v193, v97
	v_exp_f32_e32 v194, v98
	v_exp_f32_e32 v195, v99
	v_exp_f32_e32 v216, v100
	v_exp_f32_e32 v217, v101
	v_exp_f32_e32 v219, v102
	v_exp_f32_e32 v220, v103
	v_exp_f32_e32 v221, v104
	v_exp_f32_e32 v222, v105
	v_exp_f32_e32 v223, v106
	v_exp_f32_e32 v224, v107
	v_exp_f32_e32 v225, v108
	v_exp_f32_e32 v226, v109
	v_exp_f32_e32 v227, v110
	v_exp_f32_e32 v228, v111
	v_exp_f32_e32 v80, v80
	v_exp_f32_e32 v81, v81
	s_waitcnt lgkmcnt(1)
	v_mfma_f32_32x32x16_bf16 v[96:111], v[64:67], v[132:135], v[32:47]
	v_exp_f32_e32 v82, v82
	v_exp_f32_e32 v83, v83
	v_exp_f32_e32 v87, v87
	v_exp_f32_e32 v229, v92
	v_exp_f32_e32 v230, v93
	v_exp_f32_e32 v231, v94
	v_exp_f32_e32 v232, v95
	s_waitcnt lgkmcnt(0)
	v_mfma_f32_32x32x16_bf16 v[64:79], v[184:187], v[132:135], v[32:47]
	ds_read_b128 v[184:187], v244 offset:32768
	ds_read_b128 v[188:191], v244 offset:40960
	s_waitcnt lgkmcnt(1)
	v_mfma_f32_32x32x16_bf16 v[96:111], v[184:187], v[128:131], v[96:111]
	s_waitcnt lgkmcnt(0)
	v_mfma_f32_32x32x16_bf16 v[64:79], v[188:191], v[128:131], v[64:79]
	ds_read_b128 v[184:187], v245 offset:32768
	ds_read_b128 v[188:191], v245 offset:40960
	s_waitcnt lgkmcnt(1)
	v_mfma_f32_32x32x16_bf16 v[96:111], v[184:187], v[124:127], v[96:111]
	s_waitcnt lgkmcnt(0)
	v_mfma_f32_32x32x16_bf16 v[64:79], v[188:191], v[124:127], v[64:79]
	ds_read_b128 v[184:187], v246 offset:32768
	ds_read_b128 v[188:191], v246 offset:40960
	s_waitcnt lgkmcnt(1)
	v_mfma_f32_32x32x16_bf16 v[96:111], v[184:187], v[120:123], v[96:111]
	s_waitcnt lgkmcnt(0)
	v_mfma_f32_32x32x16_bf16 v[64:79], v[188:191], v[120:123], v[64:79]
	ds_read_b128 v[184:187], v247 offset:32768
	ds_read_b128 v[188:191], v247 offset:40960
	s_waitcnt lgkmcnt(1)
	v_mfma_f32_32x32x16_bf16 v[96:111], v[184:187], v[116:119], v[96:111]
	s_waitcnt lgkmcnt(0)
	v_mfma_f32_32x32x16_bf16 v[64:79], v[188:191], v[116:119], v[64:79]
	ds_read_b128 v[184:187], v248 offset:32768
	ds_read_b128 v[188:191], v248 offset:40960
	v_cvt_pk_bf16_f32 v92, v192, v193
	v_cvt_pk_bf16_f32 v93, v194, v195
	v_cvt_pk_bf16_f32 v94, v216, v217
	v_cvt_pk_bf16_f32 v95, v219, v220
	s_waitcnt lgkmcnt(1)
	v_mfma_f32_32x32x16_bf16 v[96:111], v[184:187], v[112:115], v[96:111]
	v_exp_f32_e32 v185, v84
	v_fma_f32 v84, v165, v169, v192
	v_add_f32_e32 v84, v193, v84
	v_add_f32_e32 v84, v194, v84
	v_add_f32_e32 v84, v195, v84
	v_add_f32_e32 v84, v216, v84
	v_add_f32_e32 v84, v217, v84
	v_add_f32_e32 v84, v219, v84
	v_add_f32_e32 v84, v220, v84
	v_add_f32_e32 v84, v221, v84
	v_add_f32_e32 v84, v222, v84
	v_add_f32_e32 v84, v223, v84
	v_add_f32_e32 v84, v224, v84
	v_add_f32_e32 v84, v225, v84
	v_add_f32_e32 v84, v226, v84
	v_add_f32_e32 v84, v227, v84
	v_add_f32_e32 v84, v228, v84
	v_add_f32_e32 v84, v80, v84
	v_exp_f32_e32 v186, v85
	v_add_f32_e32 v84, v81, v84
	v_exp_f32_e32 v187, v86
	v_add_f32_e32 v84, v82, v84
	v_add_f32_e32 v84, v83, v84
	s_waitcnt lgkmcnt(0)
	v_mfma_f32_32x32x16_bf16 v[64:79], v[188:191], v[112:115], v[64:79]
	v_exp_f32_e32 v188, v88
	v_add_f32_e32 v84, v185, v84
	v_exp_f32_e32 v189, v89
	v_add_f32_e32 v84, v186, v84
	v_exp_f32_e32 v190, v90
	v_add_f32_e32 v84, v187, v84
	v_exp_f32_e32 v191, v91
	v_add_f32_e32 v84, v87, v84
	v_add_f32_e32 v84, v188, v84
	v_add_f32_e32 v84, v189, v84
	v_add_f32_e32 v84, v190, v84
	v_add_f32_e32 v84, v191, v84
	v_add_f32_e32 v84, v229, v84
	v_add_f32_e32 v84, v230, v84
	v_add_f32_e32 v84, v231, v84
	v_add_f32_e32 v152, v232, v84
	v_cvt_pk_bf16_f32 v88, v221, v222
	v_cvt_pk_bf16_f32 v89, v223, v224
	v_cvt_pk_bf16_f32 v90, v225, v226
	v_cvt_pk_bf16_f32 v91, v227, v228
	v_cvt_pk_bf16_f32 v84, v80, v81
	v_cvt_pk_bf16_f32 v85, v82, v83
	v_cvt_pk_bf16_f32 v86, v185, v186
	v_cvt_pk_bf16_f32 v87, v187, v87
	v_cvt_pk_bf16_f32 v80, v188, v189
	v_cvt_pk_bf16_f32 v81, v190, v191
	v_cvt_pk_bf16_f32 v82, v229, v230
	v_cvt_pk_bf16_f32 v83, v231, v232
	s_waitcnt vmcnt(0)
	ds_write_b128 v204, v[136:139]
	ds_write_b128 v249, v[140:143]
	ds_write_b64 v250, v[172:173]

; template <bool FIRST> __device__ __forceinline__ void partialSM(f32x16& p0, f32x16& p1, float& mref, f32x16& negm, float& alpha) {
;   constexpr float THRL = THR * 1.4426950408889634f;
;   float pmax = p0[0];
; #pragma unroll
;   for (int r = 1; r < 16; ++r) pmax = fmaxf(pmax, p0[r]);
; #pragma unroll
;   for (int r = 0; r < 16; ++r) pmax = fmaxf(pmax, p1[r]);
;   { auto rr = __builtin_amdgcn_permlane32_swap(__float_as_uint(pmax), __float_as_uint(pmax), false, false);
;     pmax = fmaxf(__uint_as_float(rr[0]), __uint_as_float(rr[1])); }
;   if (!FIRST && __builtin_expect(__all(pmax <= THRL), 1)) { alpha = 1.f; }
;   else { const float dl = FIRST ? pmax : fmaxf(pmax, 0.f); mref += dl; alpha = FIRST ? 1.f : __builtin_amdgcn_exp2f(-dl);
; #pragma unroll
;     for (int r = 0; r < 16; ++r) { p0[r] -= dl; p1[r] -= dl; }
;     const float nm = -mref;
; #pragma unroll
;     for (int r = 0; r < 16; ++r) negm[r] = nm; }
; #pragma unroll
;   for (int r = 0; r < 16; ++r) p0[r] = __builtin_amdgcn_exp2f(p0[r]);
; }
; __device__ __forceinline__ void finishSM(f32x16& p0, f32x16& p1, float alpha, float& l_reg, bf16x8& pa0, bf16x8& pa1, bf16x8& pa2, bf16x8& pa3) {
; #pragma unroll
;   for (int r = 0; r < 16; ++r) p1[r] = __builtin_amdgcn_exp2f(p1[r]);
;   float ps = 0;
; #pragma unroll
;   for (int r = 0; r < 16; ++r) ps += p0[r];
; #pragma unroll
;   for (int r = 0; r < 16; ++r) ps += p1[r];
;   { auto rr = __builtin_amdgcn_permlane32_swap(__float_as_uint(ps), __float_as_uint(ps), false, false);
;     ps = __uint_as_float(rr[0]) + __uint_as_float(rr[1]); }
;   l_reg = l_reg * alpha + ps;
;     ...
;   PK4(p0, 0, pa0); PK4(p0, 8, pa1); PK4(p1, 0, pa2); PK4(p1, 8, pa3);
;     ...
; }
; __device__ __forceinline__ void qkt(f32x16& p0, f32x16& p1, const char* Ks, const bf16x8* qr, const f32x16& negm, int r32, int hi) {
;   p0 = negm; p1 = negm;
; #pragma unroll
;   for (int d0 = 0; d0 < 6; ++d0) { int cb = (d0 * 16 + hi * 8) * 2;
;     bf16x8 b0 = *reinterpret_cast<const bf16x8*>(Ks + KSWZ(r32, cb));
;     bf16x8 b1 = *reinterpret_cast<const bf16x8*>(Ks + KSWZ(32 + r32, cb));
;     p0 = __builtin_amdgcn_mfma_f32_32x32x16_bf16(b0, qr[d0], p0, 0, 0, 0);
;     p1 = __builtin_amdgcn_mfma_f32_32x32x16_bf16(b1, qr[d0], p1, 0, 0, 0); }
; }
.Lf1_755:
	v_exp_f32_e32 v194, v96
	v_exp_f32_e32 v216, v97
	v_exp_f32_e32 v192, v98
	v_exp_f32_e32 v195, v99
	v_exp_f32_e32 v190, v100
	v_exp_f32_e32 v193, v101
	v_exp_f32_e32 v189, v102
	v_exp_f32_e32 v191, v103
	v_exp_f32_e32 v186, v104
	v_exp_f32_e32 v188, v105
	v_exp_f32_e32 v185, v106
	v_exp_f32_e32 v187, v107
	v_exp_f32_e32 v181, v108
	v_exp_f32_e32 v183, v109
	v_exp_f32_e32 v180, v110
	v_exp_f32_e32 v182, v111
	s_add_i32 s90, s90, 2
	s_add_i32 s89, s89, 0x8000
	v_mov_b32_e32 v163, v84
	s_waitcnt lgkmcnt(0)
	s_barrier
	ds_read_b128 v[48:51], v243 offset:49152
	ds_read_b128 v[52:55], v243 offset:57344
	s_waitcnt lgkmcnt(1)
	v_mfma_f32_32x32x16_bf16 v[96:111], v[48:51], v[132:135], v[32:47]
	ds_read_b128 v[48:51], v244 offset:49152
	ds_read_b128 v[56:59], v244 offset:57344
	v_exp_f32_e32 v64, v64
	v_exp_f32_e32 v65, v65
	v_exp_f32_e32 v66, v66
	v_exp_f32_e32 v67, v67
	v_exp_f32_e32 v68, v68
	s_waitcnt lgkmcnt(2)
	v_mfma_f32_32x32x16_bf16 v[80:95], v[52:55], v[132:135], v[32:47]
	ds_read_b128 v[52:55], v245 offset:49152
	ds_read_b128 v[60:63], v245 offset:57344
	ds_read_b128 v[220:223], v246 offset:49152
	ds_read_b128 v[224:227], v246 offset:57344
	ds_read_b128 v[228:231], v247 offset:49152
	ds_read_b128 v[232:235], v247 offset:57344
	v_exp_f32_e32 v69, v69
	v_exp_f32_e32 v70, v70
	v_exp_f32_e32 v71, v71
	v_exp_f32_e32 v72, v72
	v_exp_f32_e32 v73, v73
	s_waitcnt lgkmcnt(7)
	v_mfma_f32_32x32x16_bf16 v[96:111], v[48:51], v[128:131], v[96:111]
	ds_read_b128 v[48:51], v248 offset:49152
	ds_read_b128 v[236:239], v248 offset:57344
	v_exp_f32_e32 v74, v74
	v_exp_f32_e32 v75, v75
	v_exp_f32_e32 v76, v76
	v_exp_f32_e32 v77, v77
	v_exp_f32_e32 v78, v78
	v_exp_f32_e32 v79, v79
	s_waitcnt lgkmcnt(8)
	v_mfma_f32_32x32x16_bf16 v[80:95], v[56:59], v[128:131], v[80:95]
	s_waitcnt lgkmcnt(7)
	v_mfma_f32_32x32x16_bf16 v[96:111], v[52:55], v[124:127], v[96:111]
	v_fma_f32 v52, v163, v152, v194
	v_add_f32_e32 v52, v216, v52
	v_add_f32_e32 v52, v192, v52
	v_add_f32_e32 v52, v195, v52
	v_add_f32_e32 v52, v190, v52
	v_add_f32_e32 v52, v193, v52
	v_add_f32_e32 v52, v189, v52
	s_waitcnt lgkmcnt(6)
	v_mfma_f32_32x32x16_bf16 v[80:95], v[60:63], v[124:127], v[80:95]
	v_add_f32_e32 v52, v191, v52
	v_add_f32_e32 v52, v186, v52
	v_add_f32_e32 v52, v188, v52
	v_add_f32_e32 v52, v185, v52
	v_add_f32_e32 v52, v187, v52
	v_add_f32_e32 v52, v181, v52
	v_add_f32_e32 v52, v183, v52
	s_waitcnt lgkmcnt(5)
	v_mfma_f32_32x32x16_bf16 v[96:111], v[220:223], v[120:123], v[96:111]
	v_add_f32_e32 v52, v180, v52
	v_add_f32_e32 v52, v182, v52
	v_add_f32_e32 v52, v64, v52
	v_add_f32_e32 v52, v65, v52
	v_add_f32_e32 v52, v66, v52
	v_add_f32_e32 v52, v67, v52
	v_add_f32_e32 v52, v68, v52
	s_waitcnt lgkmcnt(4)
	v_mfma_f32_32x32x16_bf16 v[80:95], v[224:227], v[120:123], v[80:95]
	v_add_f32_e32 v52, v69, v52
	v_add_f32_e32 v52, v70, v52
	v_add_f32_e32 v52, v71, v52
	v_add_f32_e32 v52, v72, v52
	v_add_f32_e32 v52, v73, v52
	v_add_f32_e32 v52, v74, v52
	v_add_f32_e32 v52, v75, v52
	s_waitcnt lgkmcnt(3)
	v_mfma_f32_32x32x16_bf16 v[96:111], v[228:231], v[116:119], v[96:111]
	v_add_f32_e32 v52, v76, v52
	v_add_f32_e32 v52, v77, v52
	v_add_f32_e32 v52, v78, v52
	v_add_f32_e32 v165, v79, v52
	s_waitcnt lgkmcnt(2)
	v_mfma_f32_32x32x16_bf16 v[80:95], v[232:235], v[116:119], v[80:95]
	v_cvt_pk_bf16_f32 v60, v194, v216
	v_cvt_pk_bf16_f32 v61, v192, v195
	v_cvt_pk_bf16_f32 v62, v190, v193
	v_cvt_pk_bf16_f32 v63, v189, v191
	v_cvt_pk_bf16_f32 v56, v186, v188
	v_cvt_pk_bf16_f32 v57, v185, v187
	v_cvt_pk_bf16_f32 v58, v181, v183
	s_waitcnt lgkmcnt(1)
	v_mfma_f32_32x32x16_bf16 v[96:111], v[48:51], v[112:115], v[96:111]
	v_cvt_pk_bf16_f32 v59, v180, v182
	v_cvt_pk_bf16_f32 v52, v64, v65
	v_cvt_pk_bf16_f32 v53, v66, v67
	v_cvt_pk_bf16_f32 v54, v68, v69
	v_cvt_pk_bf16_f32 v55, v70, v71
	v_cvt_pk_bf16_f32 v48, v72, v73
	v_cvt_pk_bf16_f32 v49, v74, v75
	s_waitcnt lgkmcnt(0)
	v_mfma_f32_32x32x16_bf16 v[80:95], v[236:239], v[112:115], v[80:95]
	v_cvt_pk_bf16_f32 v50, v76, v77
	v_cvt_pk_bf16_f32 v51, v78, v79
	s_waitcnt vmcnt(0)
	ds_write_b128 v204, v[144:147] offset:16384
	ds_write_b128 v249, v[148:151] offset:16384
	ds_write_b64 v250, v[174:175] offset:16384
	global_load_dwordx4 v[136:139], v240, s[98:99]
	global_load_dwordx4 v[140:143], v241, s[98:99]
	global_load_dwordx2 v[172:173], v242, s[100:101]
	s_add_u32 s98, s98, 0x10000
	s_addc_u32 s99, s99, 0
	s_add_u32 s100, s100, 0x1000
	s_addc_u32 s101, s101, 0

; template <bool FIRST> __device__ __forceinline__ void partialSM(f32x16& p0, f32x16& p1, float& mref, f32x16& negm, float& alpha) {
;   constexpr float THRL = THR * 1.4426950408889634f;
;   float pmax = p0[0];
; #pragma unroll
;   for (int r = 1; r < 16; ++r) pmax = fmaxf(pmax, p0[r]);
; #pragma unroll
;   for (int r = 0; r < 16; ++r) pmax = fmaxf(pmax, p1[r]);
;   { auto rr = __builtin_amdgcn_permlane32_swap(__float_as_uint(pmax), __float_as_uint(pmax), false, false);
;     pmax = fmaxf(__uint_as_float(rr[0]), __uint_as_float(rr[1])); }
;   if (!FIRST && __builtin_expect(__all(pmax <= THRL), 1)) { alpha = 1.f; }
;   else { const float dl = FIRST ? pmax : fmaxf(pmax, 0.f); mref += dl; alpha = FIRST ? 1.f : __builtin_amdgcn_exp2f(-dl);
; #pragma unroll
;     for (int r = 0; r < 16; ++r) { p0[r] -= dl; p1[r] -= dl; }
;     const float nm = -mref;
; #pragma unroll
;     for (int r = 0; r < 16; ++r) negm[r] = nm; }
; #pragma unroll
;   for (int r = 0; r < 16; ++r) p0[r] = __builtin_amdgcn_exp2f(p0[r]);
; }
; __device__ __forceinline__ void finishSM(f32x16& p0, f32x16& p1, float alpha, float& l_reg, bf16x8& pa0, bf16x8& pa1, bf16x8& pa2, bf16x8& pa3) {
; #pragma unroll
;   for (int r = 0; r < 16; ++r) p1[r] = __builtin_amdgcn_exp2f(p1[r]);
;   float ps = 0;
; #pragma unroll
;   for (int r = 0; r < 16; ++r) ps += p0[r];
; #pragma unroll
;   for (int r = 0; r < 16; ++r) ps += p1[r];
;   { auto rr = __builtin_amdgcn_permlane32_swap(__float_as_uint(ps), __float_as_uint(ps), false, false);
;     ps = __uint_as_float(rr[0]) + __uint_as_float(rr[1]); }
;   l_reg = l_reg * alpha + ps;
;     ...
;   PK4(p0, 0, pa0); PK4(p0, 8, pa1); PK4(p1, 0, pa2); PK4(p1, 8, pa3);
;     ...
; }
; __device__ __forceinline__ void qkt(f32x16& p0, f32x16& p1, const char* Ks, const bf16x8* qr, const f32x16& negm, int r32, int hi) {
;   p0 = negm; p1 = negm;
; #pragma unroll
;   for (int d0 = 0; d0 < 6; ++d0) { int cb = (d0 * 16 + hi * 8) * 2;
;     bf16x8 b0 = *reinterpret_cast<const bf16x8*>(Ks + KSWZ(r32, cb));
;     bf16x8 b1 = *reinterpret_cast<const bf16x8*>(Ks + KSWZ(32 + r32, cb));
;     p0 = __builtin_amdgcn_mfma_f32_32x32x16_bf16(b0, qr[d0], p0, 0, 0, 0);
;     p1 = __builtin_amdgcn_mfma_f32_32x32x16_bf16(b1, qr[d0], p1, 0, 0, 0); }
; }
.Lf2_746:
	s_waitcnt lgkmcnt(0)
	s_barrier
	ds_read_b128 v[64:67], v243
	ds_read_b128 v[184:187], v243 offset:8192
	v_exp_f32_e32 v192, v96
	v_exp_f32_e32 v193, v97
	v_exp_f32_e32 v194, v98
	v_exp_f32_e32 v195, v99
	v_exp_f32_e32 v216, v100
	v_exp_f32_e32 v217, v101
	v_exp_f32_e32 v219, v102
	v_exp_f32_e32 v220, v103
	v_exp_f32_e32 v221, v104
	v_exp_f32_e32 v222, v105
	v_exp_f32_e32 v223, v106
	v_exp_f32_e32 v224, v107
	v_exp_f32_e32 v225, v108
	v_exp_f32_e32 v226, v109
	v_exp_f32_e32 v227, v110
	v_exp_f32_e32 v228, v111
	v_exp_f32_e32 v80, v80
	v_exp_f32_e32 v81, v81
	s_waitcnt lgkmcnt(1)
	v_mfma_f32_32x32x16_bf16 v[96:111], v[64:67], v[132:135], v[32:47]
	v_exp_f32_e32 v82, v82
	v_exp_f32_e32 v83, v83
	v_exp_f32_e32 v87, v87
	v_exp_f32_e32 v229, v92
	v_exp_f32_e32 v230, v93
	v_exp_f32_e32 v231, v94
	v_exp_f32_e32 v232, v95
	s_waitcnt lgkmcnt(0)
	v_mfma_f32_32x32x16_bf16 v[64:79], v[184:187], v[132:135], v[32:47]
	ds_read_b128 v[184:187], v244
	ds_read_b128 v[188:191], v244 offset:8192
	s_waitcnt lgkmcnt(1)
	v_mfma_f32_32x32x16_bf16 v[96:111], v[184:187], v[128:131], v[96:111]
	s_waitcnt lgkmcnt(0)
	v_mfma_f32_32x32x16_bf16 v[64:79], v[188:191], v[128:131], v[64:79]
	ds_read_b128 v[184:187], v245
	ds_read_b128 v[188:191], v245 offset:8192
	s_waitcnt lgkmcnt(1)
	v_mfma_f32_32x32x16_bf16 v[96:111], v[184:187], v[124:127], v[96:111]
	s_waitcnt lgkmcnt(0)
	v_mfma_f32_32x32x16_bf16 v[64:79], v[188:191], v[124:127], v[64:79]
	ds_read_b128 v[184:187], v246
	ds_read_b128 v[188:191], v246 offset:8192
	s_waitcnt lgkmcnt(1)
	v_mfma_f32_32x32x16_bf16 v[96:111], v[184:187], v[120:123], v[96:111]
	s_waitcnt lgkmcnt(0)
	v_mfma_f32_32x32x16_bf16 v[64:79], v[188:191], v[120:123], v[64:79]
	ds_read_b128 v[184:187], v247
	ds_read_b128 v[188:191], v247 offset:8192
	s_waitcnt lgkmcnt(1)
	v_mfma_f32_32x32x16_bf16 v[96:111], v[184:187], v[116:119], v[96:111]
	s_waitcnt lgkmcnt(0)
	v_mfma_f32_32x32x16_bf16 v[64:79], v[188:191], v[116:119], v[64:79]
	ds_read_b128 v[184:187], v248
	ds_read_b128 v[188:191], v248 offset:8192
	v_cvt_pk_bf16_f32 v92, v192, v193
	v_cvt_pk_bf16_f32 v93, v194, v195
	v_cvt_pk_bf16_f32 v94, v216, v217
	v_cvt_pk_bf16_f32 v95, v219, v220
	s_waitcnt lgkmcnt(1)
	v_mfma_f32_32x32x16_bf16 v[96:111], v[184:187], v[112:115], v[96:111]
	v_exp_f32_e32 v185, v84
	v_fma_f32 v84, v165, v169, v192
	v_add_f32_e32 v84, v193, v84
	v_add_f32_e32 v84, v194, v84
	v_add_f32_e32 v84, v195, v84
	v_add_f32_e32 v84, v216, v84
	v_add_f32_e32 v84, v217, v84
	v_add_f32_e32 v84, v219, v84
	v_add_f32_e32 v84, v220, v84
	v_add_f32_e32 v84, v221, v84
	v_add_f32_e32 v84, v222, v84
	v_add_f32_e32 v84, v223, v84
	v_add_f32_e32 v84, v224, v84
	v_add_f32_e32 v84, v225, v84
	v_add_f32_e32 v84, v226, v84
	v_add_f32_e32 v84, v227, v84
	v_add_f32_e32 v84, v228, v84
	v_add_f32_e32 v84, v80, v84
	v_exp_f32_e32 v186, v85
	v_add_f32_e32 v84, v81, v84
	v_exp_f32_e32 v187, v86
	v_add_f32_e32 v84, v82, v84
	v_add_f32_e32 v84, v83, v84
	s_waitcnt lgkmcnt(0)
	v_mfma_f32_32x32x16_bf16 v[64:79], v[188:191], v[112:115], v[64:79]
	v_exp_f32_e32 v188, v88
	v_add_f32_e32 v84, v185, v84
	v_exp_f32_e32 v189, v89
	v_add_f32_e32 v84, v186, v84
	v_exp_f32_e32 v190, v90
	v_add_f32_e32 v84, v187, v84
	v_exp_f32_e32 v191, v91
	v_add_f32_e32 v84, v87, v84
	v_add_f32_e32 v84, v188, v84
	v_add_f32_e32 v84, v189, v84
	v_add_f32_e32 v84, v190, v84
	v_add_f32_e32 v84, v191, v84
	v_add_f32_e32 v84, v229, v84
	v_add_f32_e32 v84, v230, v84
	v_add_f32_e32 v84, v231, v84
	v_add_f32_e32 v152, v232, v84
	v_cvt_pk_bf16_f32 v88, v221, v222
	v_cvt_pk_bf16_f32 v89, v223, v224
	v_cvt_pk_bf16_f32 v90, v225, v226
	v_cvt_pk_bf16_f32 v91, v227, v228
	v_cvt_pk_bf16_f32 v84, v80, v81
	v_cvt_pk_bf16_f32 v85, v82, v83
	v_cvt_pk_bf16_f32 v86, v185, v186
	v_cvt_pk_bf16_f32 v87, v187, v87
	v_cvt_pk_bf16_f32 v80, v188, v189
	v_cvt_pk_bf16_f32 v81, v190, v191
	v_cvt_pk_bf16_f32 v82, v229, v230
	v_cvt_pk_bf16_f32 v83, v231, v232
	s_waitcnt vmcnt(0)
	ds_write_b128 v204, v[136:139] offset:32768
	ds_write_b128 v249, v[140:143] offset:32768
	ds_write_b64 v250, v[172:173] offset:32768
